# combo: ph3 reassign, attention vmcnt fix, early priority raise in all K-loops, SGPR-base LDS-DMA addressing in gate/up K-loop
# speedup vs baseline: 1.0018x; 1.0018x over previous
; #define PG8_STAGE(bufoff, gbase, voff) do { _Pragma("unroll") for (int _i = 0; _i < 2; ++_i) \
;         __builtin_amdgcn_global_load_lds((const unsigned*)((const char*)(gbase) + (voff)[_i]), (PG8_LAS unsigned*)(lds + (bufoff) + ldsw + _i * 8192), 16, 0, 0); } while (0)
; #define PG8_LDA(dst, b, h) do { _Pragma("unroll") for (int m = 0; m < 4; ++m) _Pragma("unroll") for (int k = 0; k < 2; ++k) dst[m][k] = *(const PG8_LAS bf16x8*)(lds + PG8_SA(b, h) + aoff + m * 2048 + k * 1024); } while (0)
; #define PG8_LDB(dst, b, h) do { _Pragma("unroll") for (int n = 0; n < 2; ++n) _Pragma("unroll") for (int k = 0; k < 2; ++k) dst[n][k] = *(const PG8_LAS bf16x8*)(lds + PG8_SB(b, h) + boff + n * 2048 + k * 1024); } while (0)
; #define PG8_MMA(ai, bj, At, Bt) do { __builtin_amdgcn_s_setprio(1); _Pragma("unroll") for (int m = 0; m < 4; ++m) _Pragma("unroll") for (int n = 0; n < 2; ++n) _Pragma("unroll") for (int k = 0; k < 2; ++k) \
;         acc[ai][bj][m][n] = __builtin_amdgcn_mfma_f32_16x16x32_bf16(Bt[n][k], At[m][k], acc[ai][bj][m][n], 0, 0, 0); __builtin_amdgcn_s_setprio(0); } while (0)
; #define PG8_WAIT_V(n) asm volatile("s_waitcnt vmcnt(" #n ")" ::: "memory")
; #define PG8_WAIT_L(n) asm volatile("s_waitcnt lgkmcnt(" #n ")" ::: "memory")
; template <class Epi, class Sched, bool ALIGN_EPI = false, bool SP2 = false>
; __device__ __forceinline__ void gemm_phase(PG8_LAS unsigned char* lds, const Gemm g, const Sched& S, const Epi& E) {
;     ...
;             const bool last = (t == nt - 2);
;             const char* a1 = cA + (size_t)(t + 1) * kstep;
;             const char* a2 = last ? nA : cA + (size_t)(t + 2) * kstep; const char* b2 = last ? nB : cB + (size_t)(t + 2) * kstep;
;             const char* a3 = a2 + kstep; const char* b3 = b2 + kstep;
;             if (last && has_next) S.a_ready(nxt);
;             if constexpr (SP2) {
;             PG8_LDB(B0, 0, 0); PG8_LDB(B1, 0, 1); PG8_SCHED; PG8_LDA(At, 0, 0); PG8_STAGE(PG8_SA(1, 1), a1 + hstep, voffA);
;             PG8_WAIT_V(8); PG8_WAIT_L(0); PG8_BAR; PG8_MMA(0, 0, At, B0); PG8_MMA(0, 1, At, B1); PG8_BAR; PG8_SCHED;
;             PG8_LDA(At, 0, 1); PG8_STAGE(PG8_SB(0, 0), b2, voffB); PG8_STAGE(PG8_SB(0, 1), b2 + hstep, voffB); PG8_STAGE(PG8_SA(0, 0), a2, voffA);
;             PG8_WAIT_V(8); PG8_WAIT_L(0); PG8_BAR; PG8_MMA(1, 0, At, B0); PG8_MMA(1, 1, At, B1); PG8_BAR; PG8_SCHED;
.LBB0_431:
	s_add_u32 s54, s42, s52
	s_addc_u32 s55, s43, s53
	s_add_u32 s54, s54, 0x100
	s_addc_u32 s55, s55, 0
	s_add_u32 s75, s29, s52
	s_addc_u32 s76, s33, s53
	s_cmpk_eq_i32 s52, 0xf00
	s_cselect_b32 s57, s25, s55
	s_cselect_b32 s56, s47, s54
	s_cselect_b32 s55, s45, s76
	s_cselect_b32 s54, s73, s75
	s_add_i32 s75, 0, 0x10000
	v_add_u32_e32 v152, s75, v145
	s_add_i32 s78, 0, 0x14000
	ds_read_b128 v[148:151], v152
	ds_read_b128 v[170:173], v152 offset:1024
	ds_read_b128 v[174:177], v152 offset:2048
	ds_read_b128 v[178:181], v152 offset:3072
	v_add_u32_e32 v152, s78, v145
	ds_read_b128 v[182:185], v152
	ds_read_b128 v[186:189], v152 offset:1024
	ds_read_b128 v[190:193], v152 offset:2048
	ds_read_b128 v[194:197], v152 offset:3072
	s_add_u32 s76, s42, s52
	s_addc_u32 s77, s43, s53
	s_add_u32 s76, s76, 0x80080
	s_addc_u32 s77, s77, 0
	s_add_i32 m0, s15, 0xc000
	ds_read_b128 v[198:201], v147
	ds_read_b128 v[202:205], v147 offset:1024
	ds_read_b128 v[206:209], v147 offset:2048
	ds_read_b128 v[210:213], v147 offset:3072
	ds_read_b128 v[220:223], v147 offset:4096
	ds_read_b128 v[224:227], v147 offset:5120
	ds_read_b128 v[228:231], v147 offset:6144
	ds_read_b128 v[232:235], v147 offset:7168
	global_load_lds_dwordx4 v136, s[76:77]
	s_add_i32 m0, s15, 0xe000
	s_nop 0
	global_load_lds_dwordx4 v138, s[76:77]
	s_waitcnt vmcnt(8)
	s_waitcnt lgkmcnt(0)
	s_setprio 1
	s_barrier
	s_waitcnt lgkmcnt(0)
	v_mfma_f32_16x16x32_bf16 v[124:127], v[148:151], v[198:201], v[124:127]
	v_mfma_f32_16x16x32_bf16 v[120:123], v[174:177], v[198:201], v[120:123]
	v_mfma_f32_16x16x32_bf16 v[116:119], v[148:151], v[206:209], v[116:119]
	v_mfma_f32_16x16x32_bf16 v[112:115], v[174:177], v[206:209], v[112:115]
	v_mfma_f32_16x16x32_bf16 v[108:111], v[148:151], v[220:223], v[108:111]
	v_mfma_f32_16x16x32_bf16 v[104:107], v[174:177], v[220:223], v[104:107]
	v_mfma_f32_16x16x32_bf16 v[100:103], v[148:151], v[228:231], v[100:103]
	v_mfma_f32_16x16x32_bf16 v[96:99], v[174:177], v[228:231], v[96:99]
	v_mfma_f32_16x16x32_bf16 v[124:127], v[170:173], v[202:205], v[124:127]
	v_mfma_f32_16x16x32_bf16 v[120:123], v[178:181], v[202:205], v[120:123]
	v_mfma_f32_16x16x32_bf16 v[116:119], v[170:173], v[210:213], v[116:119]
	v_mfma_f32_16x16x32_bf16 v[112:115], v[178:181], v[210:213], v[112:115]
	v_mfma_f32_16x16x32_bf16 v[108:111], v[170:173], v[224:227], v[108:111]
	v_mfma_f32_16x16x32_bf16 v[104:107], v[178:181], v[224:227], v[104:107]
	v_mfma_f32_16x16x32_bf16 v[100:103], v[170:173], v[232:235], v[100:103]
	v_mfma_f32_16x16x32_bf16 v[96:99], v[178:181], v[232:235], v[96:99]
	s_setprio 0
	s_setprio 1
	v_mfma_f32_16x16x32_bf16 v[92:95], v[182:185], v[198:201], v[92:95]
	v_mfma_f32_16x16x32_bf16 v[88:91], v[190:193], v[198:201], v[88:91]
	v_mfma_f32_16x16x32_bf16 v[84:87], v[182:185], v[206:209], v[84:87]
	v_mfma_f32_16x16x32_bf16 v[80:83], v[190:193], v[206:209], v[80:83]
	v_mfma_f32_16x16x32_bf16 v[76:79], v[182:185], v[220:223], v[76:79]
	v_mfma_f32_16x16x32_bf16 v[72:75], v[190:193], v[220:223], v[72:75]
	v_mfma_f32_16x16x32_bf16 v[68:71], v[182:185], v[228:231], v[68:71]
	v_mfma_f32_16x16x32_bf16 v[64:67], v[190:193], v[228:231], v[64:67]
	v_mfma_f32_16x16x32_bf16 v[92:95], v[186:189], v[202:205], v[92:95]
	v_mfma_f32_16x16x32_bf16 v[88:91], v[194:197], v[202:205], v[88:91]
	v_mfma_f32_16x16x32_bf16 v[84:87], v[186:189], v[210:213], v[84:87]
	v_mfma_f32_16x16x32_bf16 v[80:83], v[194:197], v[210:213], v[80:83]
	v_mfma_f32_16x16x32_bf16 v[76:79], v[186:189], v[224:227], v[76:79]
	v_mfma_f32_16x16x32_bf16 v[72:75], v[194:197], v[224:227], v[72:75]
	v_mfma_f32_16x16x32_bf16 v[68:71], v[186:189], v[232:235], v[68:71]
	v_mfma_f32_16x16x32_bf16 v[64:67], v[194:197], v[232:235], v[64:67]
	s_setprio 0
	s_barrier
	s_add_i32 s75, s75, s65
	s_mov_b32 m0, s75
	ds_read_b128 v[198:201], v147 offset:16384
	ds_read_b128 v[202:205], v147 offset:17408
	ds_read_b128 v[206:209], v147 offset:18432
	ds_read_b128 v[210:213], v147 offset:19456
	ds_read_b128 v[220:223], v147 offset:20480
	ds_read_b128 v[224:227], v147 offset:21504
	ds_read_b128 v[228:231], v147 offset:22528
	ds_read_b128 v[232:235], v147 offset:23552
	global_load_lds_dwordx4 v130, s[54:55]
	s_add_i32 m0, s75, 0x2000
	s_add_u32 s76, s54, 0x80000
	s_addc_u32 s77, s55, 0
	s_add_i32 s75, s78, s65
	global_load_lds_dwordx4 v134, s[54:55]
	s_mov_b32 m0, s75
	s_nop 0
	global_load_lds_dwordx4 v130, s[76:77]
	s_add_i32 m0, s75, 0x2000
	s_nop 0
	global_load_lds_dwordx4 v134, s[76:77]
	s_mov_b32 m0, s15
	s_nop 0
	global_load_lds_dwordx4 v128, s[56:57]
	s_mov_b32 m0, s17
	s_nop 0
	global_load_lds_dwordx4 v132, s[56:57]
	s_waitcnt vmcnt(8)
	s_waitcnt lgkmcnt(0)
	s_setprio 1
	s_barrier
; #define PG8_STAGE(bufoff, gbase, voff) do { _Pragma("unroll") for (int _i = 0; _i < 2; ++_i) \
;         __builtin_amdgcn_global_load_lds((const unsigned*)((const char*)(gbase) + (voff)[_i]), (PG8_LAS unsigned*)(lds + (bufoff) + ldsw + _i * 8192), 16, 0, 0); } while (0)
; #define PG8_LDA(dst, b, h) do { _Pragma("unroll") for (int m = 0; m < 4; ++m) _Pragma("unroll") for (int k = 0; k < 2; ++k) dst[m][k] = *(const PG8_LAS bf16x8*)(lds + PG8_SA(b, h) + aoff + m * 2048 + k * 1024); } while (0)
; #define PG8_LDB(dst, b, h) do { _Pragma("unroll") for (int n = 0; n < 2; ++n) _Pragma("unroll") for (int k = 0; k < 2; ++k) dst[n][k] = *(const PG8_LAS bf16x8*)(lds + PG8_SB(b, h) + boff + n * 2048 + k * 1024); } while (0)
; #define PG8_MMA(ai, bj, At, Bt) do { __builtin_amdgcn_s_setprio(1); _Pragma("unroll") for (int m = 0; m < 4; ++m) _Pragma("unroll") for (int n = 0; n < 2; ++n) _Pragma("unroll") for (int k = 0; k < 2; ++k) \
;         acc[ai][bj][m][n] = __builtin_amdgcn_mfma_f32_16x16x32_bf16(Bt[n][k], At[m][k], acc[ai][bj][m][n], 0, 0, 0); __builtin_amdgcn_s_setprio(0); } while (0)
; #define PG8_WAIT_V(n) asm volatile("s_waitcnt vmcnt(" #n ")" ::: "memory")
; #define PG8_WAIT_L(n) asm volatile("s_waitcnt lgkmcnt(" #n ")" ::: "memory")
; #define PG8_BAR __builtin_amdgcn_s_barrier()
; #define PG8_SCHED __builtin_amdgcn_sched_barrier(0)
; template <class Epi, class Sched, bool ALIGN_EPI = false, bool SP2 = false>
; __device__ __forceinline__ void gemm_phase(PG8_LAS unsigned char* lds, const Gemm g, const Sched& S, const Epi& E) {
;     ...
;             PG8_WAIT_V(8); PG8_WAIT_L(0); PG8_BAR; PG8_MMA(1, 0, At, B0); PG8_MMA(1, 1, At, B1); PG8_BAR; PG8_SCHED;
;             PG8_LDB(B0, 1, 0); PG8_LDB(B1, 1, 1); PG8_SCHED; PG8_LDA(At, 1, 0); PG8_STAGE(PG8_SA(0, 1), a2 + hstep, voffA);
;             PG8_WAIT_V(8); PG8_WAIT_L(0); PG8_BAR; PG8_MMA(0, 0, At, B0); PG8_MMA(0, 1, At, B1); PG8_BAR; PG8_SCHED;
	s_waitcnt lgkmcnt(0)
	v_mfma_f32_16x16x32_bf16 v[60:63], v[148:151], v[198:201], v[60:63]
	v_mfma_f32_16x16x32_bf16 v[56:59], v[174:177], v[198:201], v[56:59]
	v_mfma_f32_16x16x32_bf16 v[52:55], v[148:151], v[206:209], v[52:55]
	v_mfma_f32_16x16x32_bf16 v[48:51], v[174:177], v[206:209], v[48:51]
	v_mfma_f32_16x16x32_bf16 v[44:47], v[148:151], v[220:223], v[44:47]
	v_mfma_f32_16x16x32_bf16 v[40:43], v[174:177], v[220:223], v[40:43]
	v_mfma_f32_16x16x32_bf16 v[36:39], v[148:151], v[228:231], v[36:39]
	v_mfma_f32_16x16x32_bf16 v[32:35], v[174:177], v[228:231], v[32:35]
	v_mfma_f32_16x16x32_bf16 v[60:63], v[170:173], v[202:205], v[60:63]
	v_mfma_f32_16x16x32_bf16 v[56:59], v[178:181], v[202:205], v[56:59]
	v_mfma_f32_16x16x32_bf16 v[52:55], v[170:173], v[210:213], v[52:55]
	v_mfma_f32_16x16x32_bf16 v[48:51], v[178:181], v[210:213], v[48:51]
	v_mfma_f32_16x16x32_bf16 v[44:47], v[170:173], v[224:227], v[44:47]
	v_mfma_f32_16x16x32_bf16 v[40:43], v[178:181], v[224:227], v[40:43]
	v_mfma_f32_16x16x32_bf16 v[36:39], v[170:173], v[232:235], v[36:39]
	v_mfma_f32_16x16x32_bf16 v[32:35], v[178:181], v[232:235], v[32:35]
	s_setprio 0
	s_setprio 1
	v_mfma_f32_16x16x32_bf16 v[28:31], v[182:185], v[198:201], v[28:31]
	v_mfma_f32_16x16x32_bf16 v[24:27], v[190:193], v[198:201], v[24:27]
	v_mfma_f32_16x16x32_bf16 v[20:23], v[182:185], v[206:209], v[20:23]
	v_mfma_f32_16x16x32_bf16 v[16:19], v[190:193], v[206:209], v[16:19]
	v_mfma_f32_16x16x32_bf16 v[12:15], v[182:185], v[220:223], v[12:15]
	v_mfma_f32_16x16x32_bf16 v[8:11], v[190:193], v[220:223], v[8:11]
	v_mfma_f32_16x16x32_bf16 v[4:7], v[182:185], v[228:231], v[4:7]
	v_mfma_f32_16x16x32_bf16 v[0:3], v[190:193], v[228:231], v[0:3]
	v_mfma_f32_16x16x32_bf16 v[28:31], v[186:189], v[202:205], v[28:31]
	v_mfma_f32_16x16x32_bf16 v[24:27], v[194:197], v[202:205], v[24:27]
	v_mfma_f32_16x16x32_bf16 v[20:23], v[186:189], v[210:213], v[20:23]
	v_mfma_f32_16x16x32_bf16 v[16:19], v[194:197], v[210:213], v[16:19]
	v_mfma_f32_16x16x32_bf16 v[12:15], v[186:189], v[224:227], v[12:15]
	v_mfma_f32_16x16x32_bf16 v[8:11], v[194:197], v[224:227], v[8:11]
	v_mfma_f32_16x16x32_bf16 v[4:7], v[186:189], v[232:235], v[4:7]
	v_mfma_f32_16x16x32_bf16 v[0:3], v[194:197], v[232:235], v[0:3]
	s_setprio 0
	s_barrier
	s_add_i32 s75, 0, 0x18000
	v_add_u32_e32 v152, s75, v145
	s_add_i32 s76, 0, 0x1c000
	ds_read_b128 v[148:151], v152
	ds_read_b128 v[170:173], v152 offset:1024
	ds_read_b128 v[174:177], v152 offset:2048
	ds_read_b128 v[178:181], v152 offset:3072
	v_add_u32_e32 v152, s76, v145
	ds_read_b128 v[182:185], v152
	ds_read_b128 v[186:189], v152 offset:1024
	ds_read_b128 v[190:193], v152 offset:2048
	ds_read_b128 v[194:197], v152 offset:3072
	s_add_u32 s56, s56, 0x80000
	s_addc_u32 s57, s57, 0
	s_mov_b32 m0, s68
	ds_read_b128 v[198:201], v147 offset:32768
	ds_read_b128 v[202:205], v147 offset:33792
	ds_read_b128 v[206:209], v147 offset:34816
	ds_read_b128 v[210:213], v147 offset:35840
	ds_read_b128 v[220:223], v147 offset:36864
	ds_read_b128 v[224:227], v147 offset:37888
	ds_read_b128 v[228:231], v147 offset:38912
	ds_read_b128 v[232:235], v147 offset:39936
	global_load_lds_dwordx4 v128, s[56:57]
	s_mov_b32 m0, s69
	s_nop 0
	global_load_lds_dwordx4 v132, s[56:57]
	s_waitcnt vmcnt(8)
	s_waitcnt lgkmcnt(0)
	s_setprio 1
	s_barrier
	s_waitcnt lgkmcnt(0)
	v_mfma_f32_16x16x32_bf16 v[124:127], v[148:151], v[198:201], v[124:127]
	v_mfma_f32_16x16x32_bf16 v[120:123], v[174:177], v[198:201], v[120:123]
	v_mfma_f32_16x16x32_bf16 v[116:119], v[148:151], v[206:209], v[116:119]
	v_mfma_f32_16x16x32_bf16 v[112:115], v[174:177], v[206:209], v[112:115]
	v_mfma_f32_16x16x32_bf16 v[108:111], v[148:151], v[220:223], v[108:111]
	v_mfma_f32_16x16x32_bf16 v[104:107], v[174:177], v[220:223], v[104:107]
	v_mfma_f32_16x16x32_bf16 v[100:103], v[148:151], v[228:231], v[100:103]
	v_mfma_f32_16x16x32_bf16 v[96:99], v[174:177], v[228:231], v[96:99]
	v_mfma_f32_16x16x32_bf16 v[124:127], v[170:173], v[202:205], v[124:127]
	v_mfma_f32_16x16x32_bf16 v[120:123], v[178:181], v[202:205], v[120:123]
	v_mfma_f32_16x16x32_bf16 v[116:119], v[170:173], v[210:213], v[116:119]
	v_mfma_f32_16x16x32_bf16 v[112:115], v[178:181], v[210:213], v[112:115]
	v_mfma_f32_16x16x32_bf16 v[108:111], v[170:173], v[224:227], v[108:111]
	v_mfma_f32_16x16x32_bf16 v[104:107], v[178:181], v[224:227], v[104:107]
	v_mfma_f32_16x16x32_bf16 v[100:103], v[170:173], v[232:235], v[100:103]
	v_mfma_f32_16x16x32_bf16 v[96:99], v[178:181], v[232:235], v[96:99]
	s_setprio 0
	s_setprio 1
	v_mfma_f32_16x16x32_bf16 v[92:95], v[182:185], v[198:201], v[92:95]
	v_mfma_f32_16x16x32_bf16 v[88:91], v[190:193], v[198:201], v[88:91]
	v_mfma_f32_16x16x32_bf16 v[84:87], v[182:185], v[206:209], v[84:87]
	v_mfma_f32_16x16x32_bf16 v[80:83], v[190:193], v[206:209], v[80:83]
	v_mfma_f32_16x16x32_bf16 v[76:79], v[182:185], v[220:223], v[76:79]
	v_mfma_f32_16x16x32_bf16 v[72:75], v[190:193], v[220:223], v[72:75]
	v_mfma_f32_16x16x32_bf16 v[68:71], v[182:185], v[228:231], v[68:71]
	v_mfma_f32_16x16x32_bf16 v[64:67], v[190:193], v[228:231], v[64:67]
	v_mfma_f32_16x16x32_bf16 v[92:95], v[186:189], v[202:205], v[92:95]
	v_mfma_f32_16x16x32_bf16 v[88:91], v[194:197], v[202:205], v[88:91]
	v_mfma_f32_16x16x32_bf16 v[84:87], v[186:189], v[210:213], v[84:87]
	v_mfma_f32_16x16x32_bf16 v[80:83], v[194:197], v[210:213], v[80:83]
	v_mfma_f32_16x16x32_bf16 v[76:79], v[186:189], v[224:227], v[76:79]
	v_mfma_f32_16x16x32_bf16 v[72:75], v[194:197], v[224:227], v[72:75]
	v_mfma_f32_16x16x32_bf16 v[68:71], v[186:189], v[232:235], v[68:71]
	v_mfma_f32_16x16x32_bf16 v[64:67], v[194:197], v[232:235], v[64:67]
	s_setprio 0
	s_barrier
; #define PG8_STAGE(bufoff, gbase, voff) do { _Pragma("unroll") for (int _i = 0; _i < 2; ++_i) \
;         __builtin_amdgcn_global_load_lds((const unsigned*)((const char*)(gbase) + (voff)[_i]), (PG8_LAS unsigned*)(lds + (bufoff) + ldsw + _i * 8192), 16, 0, 0); } while (0)
; #define PG8_LDA(dst, b, h) do { _Pragma("unroll") for (int m = 0; m < 4; ++m) _Pragma("unroll") for (int k = 0; k < 2; ++k) dst[m][k] = *(const PG8_LAS bf16x8*)(lds + PG8_SA(b, h) + aoff + m * 2048 + k * 1024); } while (0)
; #define PG8_MMA(ai, bj, At, Bt) do { __builtin_amdgcn_s_setprio(1); _Pragma("unroll") for (int m = 0; m < 4; ++m) _Pragma("unroll") for (int n = 0; n < 2; ++n) _Pragma("unroll") for (int k = 0; k < 2; ++k) \
;         acc[ai][bj][m][n] = __builtin_amdgcn_mfma_f32_16x16x32_bf16(Bt[n][k], At[m][k], acc[ai][bj][m][n], 0, 0, 0); __builtin_amdgcn_s_setprio(0); } while (0)
; #define PG8_WAIT_V(n) asm volatile("s_waitcnt vmcnt(" #n ")" ::: "memory")
; #define PG8_WAIT_L(n) asm volatile("s_waitcnt lgkmcnt(" #n ")" ::: "memory")
; #define PG8_BAR __builtin_amdgcn_s_barrier()
; #define PG8_SCHED __builtin_amdgcn_sched_barrier(0)
; template <class Epi, class Sched, bool ALIGN_EPI = false, bool SP2 = false>
; __device__ __forceinline__ void gemm_phase(PG8_LAS unsigned char* lds, const Gemm g, const Sched& S, const Epi& E) {
;     ...
;         for (int t = 0; t < nt; t += 2) {
;             const bool last = (t == nt - 2);
;             const char* a1 = cA + (size_t)(t + 1) * kstep;
;             const char* a2 = last ? nA : cA + (size_t)(t + 2) * kstep; const char* b2 = last ? nB : cB + (size_t)(t + 2) * kstep;
;     ...
;             PG8_LDA(At, 1, 1); PG8_STAGE(PG8_SB(1, 0), b3, voffB); PG8_STAGE(PG8_SB(1, 1), b3 + hstep, voffB); PG8_STAGE(PG8_SA(1, 0), a3, voffA);
;             PG8_WAIT_V(8); PG8_WAIT_L(0); PG8_BAR; PG8_MMA(1, 0, At, B0); PG8_MMA(1, 1, At, B1); PG8_BAR; PG8_SCHED;
	s_add_i32 s78, s75, s65
	s_add_u32 s54, s54, 0x80
	s_addc_u32 s55, s55, 0
	s_mov_b32 m0, s78
	ds_read_b128 v[198:201], v147 offset:49152
	ds_read_b128 v[202:205], v147 offset:50176
	ds_read_b128 v[206:209], v147 offset:51200
	ds_read_b128 v[210:213], v147 offset:52224
	ds_read_b128 v[220:223], v147 offset:53248
	ds_read_b128 v[224:227], v147 offset:54272
	ds_read_b128 v[228:231], v147 offset:55296
	ds_read_b128 v[232:235], v147 offset:56320
	global_load_lds_dwordx4 v130, s[54:55]
	s_add_i32 m0, s78, 0x2000
	s_add_i32 s78, s76, s65
	global_load_lds_dwordx4 v134, s[54:55]
	s_add_u32 s54, s54, 0x80000
	s_addc_u32 s55, s55, 0
	s_mov_b32 m0, s78
	s_nop 0
	global_load_lds_dwordx4 v130, s[54:55]
	s_add_i32 m0, s78, 0x2000
	s_sub_u32 s56, s56, 0x7ff80
	s_subb_u32 s57, s57, 0
	global_load_lds_dwordx4 v134, s[54:55]
	s_mov_b32 m0, s70
	s_nop 0
	global_load_lds_dwordx4 v128, s[56:57]
	s_mov_b32 m0, s71
	s_nop 0
	global_load_lds_dwordx4 v132, s[56:57]
	s_waitcnt vmcnt(8)
	s_waitcnt lgkmcnt(0)
	s_setprio 1
	s_barrier
	s_waitcnt lgkmcnt(0)
	v_mfma_f32_16x16x32_bf16 v[60:63], v[148:151], v[198:201], v[60:63]
	v_mfma_f32_16x16x32_bf16 v[56:59], v[174:177], v[198:201], v[56:59]
	v_mfma_f32_16x16x32_bf16 v[52:55], v[148:151], v[206:209], v[52:55]
	v_mfma_f32_16x16x32_bf16 v[48:51], v[174:177], v[206:209], v[48:51]
	v_mfma_f32_16x16x32_bf16 v[44:47], v[148:151], v[220:223], v[44:47]
	v_mfma_f32_16x16x32_bf16 v[40:43], v[174:177], v[220:223], v[40:43]
	v_mfma_f32_16x16x32_bf16 v[36:39], v[148:151], v[228:231], v[36:39]
	v_mfma_f32_16x16x32_bf16 v[32:35], v[174:177], v[228:231], v[32:35]
	v_mfma_f32_16x16x32_bf16 v[60:63], v[170:173], v[202:205], v[60:63]
	v_mfma_f32_16x16x32_bf16 v[56:59], v[178:181], v[202:205], v[56:59]
	v_mfma_f32_16x16x32_bf16 v[52:55], v[170:173], v[210:213], v[52:55]
	v_mfma_f32_16x16x32_bf16 v[48:51], v[178:181], v[210:213], v[48:51]
	v_mfma_f32_16x16x32_bf16 v[44:47], v[170:173], v[224:227], v[44:47]
	v_mfma_f32_16x16x32_bf16 v[40:43], v[178:181], v[224:227], v[40:43]
	v_mfma_f32_16x16x32_bf16 v[36:39], v[170:173], v[232:235], v[36:39]
	v_mfma_f32_16x16x32_bf16 v[32:35], v[178:181], v[232:235], v[32:35]
	s_setprio 0
	s_setprio 1
	v_mfma_f32_16x16x32_bf16 v[28:31], v[182:185], v[198:201], v[28:31]
	v_mfma_f32_16x16x32_bf16 v[24:27], v[190:193], v[198:201], v[24:27]
	v_mfma_f32_16x16x32_bf16 v[20:23], v[182:185], v[206:209], v[20:23]
	v_mfma_f32_16x16x32_bf16 v[16:19], v[190:193], v[206:209], v[16:19]
	v_mfma_f32_16x16x32_bf16 v[12:15], v[182:185], v[220:223], v[12:15]
	v_mfma_f32_16x16x32_bf16 v[8:11], v[190:193], v[220:223], v[8:11]
	v_mfma_f32_16x16x32_bf16 v[4:7], v[182:185], v[228:231], v[4:7]
	v_mfma_f32_16x16x32_bf16 v[0:3], v[190:193], v[228:231], v[0:3]
	v_mfma_f32_16x16x32_bf16 v[28:31], v[186:189], v[202:205], v[28:31]
	v_mfma_f32_16x16x32_bf16 v[24:27], v[194:197], v[202:205], v[24:27]
	v_mfma_f32_16x16x32_bf16 v[20:23], v[186:189], v[210:213], v[20:23]
	v_mfma_f32_16x16x32_bf16 v[16:19], v[194:197], v[210:213], v[16:19]
	v_mfma_f32_16x16x32_bf16 v[12:15], v[186:189], v[224:227], v[12:15]
	v_mfma_f32_16x16x32_bf16 v[8:11], v[194:197], v[224:227], v[8:11]
	v_mfma_f32_16x16x32_bf16 v[4:7], v[186:189], v[232:235], v[4:7]
	v_mfma_f32_16x16x32_bf16 v[0:3], v[194:197], v[232:235], v[0:3]
	s_setprio 0
	s_barrier
	s_add_i32 s74, s74, 2
	s_add_u32 s52, s52, 0x100
	s_addc_u32 s53, s53, 0
	s_cmp_gt_u32 s74, 29
	s_cbranch_scc0 .LBB0_431
	s_and_b64 vcc, exec, s[26:27]
	s_cbranch_vccz .LBB0_434
	s_barrier
